# scan: next-chunk decay products (SC_DECAY) moved from the tail of level 9 to its head (bpermute issued before the level's LDS reads, masked scaling + wtot write after the first full LDS wait); on top
# baseline (speedup 1.0000x reference)
.LBB0_866:
	s_waitcnt lgkmcnt(0)
	s_barrier
	v_add_u32_e32 v18, v70, v71
	v_bfe_u32 v172, v0, 2, 2
	v_mul_u32_u24_e32 v172, 0x90, v172
	v_add_u32_e32 v173, v18, v172
	v_add_u32_e32 v174, v83, v172
	v_add_u32_e32 v175, v84, v172
	ds_read_b64_tr_b16 v[10:11], v173
	ds_read_b64_tr_b16 v[12:13], v173 offset:144
	ds_read_b64_tr_b16 v[14:15], v174 offset:18432
	ds_read_b64_tr_b16 v[16:17], v174 offset:18576
	ds_read_b64_tr_b16 v[122:123], v173 offset:4608
	ds_read_b64_tr_b16 v[124:125], v173 offset:4752
	ds_read_b64_tr_b16 v[22:23], v174 offset:23184
	ds_read_b64_tr_b16 v[20:21], v174 offset:23040
	ds_read_b64_tr_b16 v[130:131], v174 offset:27648
	ds_read_b64_tr_b16 v[132:133], v174 offset:27792
	ds_read_b64_tr_b16 v[136:137], v174 offset:32400
	ds_read_b64_tr_b16 v[134:135], v174 offset:32256
	ds_read_b64_tr_b16 v[142:143], v173 offset:9216
	ds_read_b64_tr_b16 v[144:145], v173 offset:9360
	ds_read_b64_tr_b16 v[146:147], v173 offset:13824
	ds_read_b64_tr_b16 v[148:149], v173 offset:13968
	s_waitcnt lgkmcnt(12)
	v_mfma_f32_16x16x32_bf16 v[126:129], v[10:13], v[14:17], 0
	ds_read_b64_tr_b16 v[152:153], v175 offset:23184
	ds_read_b64_tr_b16 v[154:155], v175 offset:27648
	ds_read_b64_tr_b16 v[156:157], v175 offset:27792
	ds_read_b64_tr_b16 v[158:159], v175 offset:32256
	v_mov_b32_e32 v24, s29
	v_mov_b32_e32 v64, s29
	s_waitcnt lgkmcnt(6)
	v_mfma_f32_16x16x32_bf16 v[14:17], v[142:145], v[14:17], 0
	v_readlane_b32 s12, v250, 5
	v_readlane_b32 s26, v250, 19
	v_readlane_b32 s27, v250, 20
	v_mfma_f32_16x16x32_bf16 v[126:129], v[122:125], v[20:23], v[126:129]
	s_andn2_b64 vcc, exec, s[10:11]
	v_readlane_b32 s13, v250, 6
	v_readlane_b32 s14, v250, 7
	v_mfma_f32_16x16x32_bf16 v[138:141], v[10:13], v[130:133], 0
	v_readlane_b32 s15, v250, 8
	s_nop 2
	v_cndmask_b32_e64 v25, v24, v126, s[58:59]
	v_cndmask_b32_e64 v65, v127, 0, s[60:61]
	s_waitcnt lgkmcnt(4)
	v_mfma_f32_16x16x32_bf16 v[14:17], v[146:149], v[20:23], v[14:17]
	v_readlane_b32 s16, v250, 9
	v_readlane_b32 s17, v250, 10
	v_readlane_b32 s18, v250, 11
	v_mfma_f32_16x16x32_bf16 v[20:23], v[142:145], v[130:133], 0
	ds_read_b64_tr_b16 v[130:131], v175 offset:18432
	ds_read_b64_tr_b16 v[132:133], v175 offset:18576
	ds_read_b64_tr_b16 v[150:151], v175 offset:23040
	ds_read_b64_tr_b16 v[160:161], v175 offset:32400
	v_cndmask_b32_e64 v24, v14, v24, s[60:61]
	v_cndmask_b32_e64 v126, v15, 0, s[62:63]
	v_mfma_f32_16x16x32_bf16 v[138:141], v[122:125], v[134:137], v[138:141]
	v_cvt_pk_bf16_f32 v14, v25, v65
	v_readlane_b32 s19, v250, 12
	v_readlane_b32 s20, v250, 13
	v_mfma_f32_16x16x32_bf16 v[20:23], v[146:149], v[134:137], v[20:23]
	v_cndmask_b32_e64 v134, 0, v128, s[64:65]
	s_nop 2
	v_cndmask_b32_e64 v19, v64, v138, s[58:59]
	v_cndmask_b32_e64 v135, 0, v141, s[68:69]
	v_cndmask_b32_e64 v136, 0, v129, s[68:69]
	v_cndmask_b32_e64 v128, v16, 0, s[66:67]
	v_cndmask_b32_e64 v64, v20, v64, s[60:61]
	v_cndmask_b32_e64 v20, v139, 0, s[60:61]
	v_cndmask_b32_e64 v121, v21, 0, s[62:63]
	v_cndmask_b32_e64 v21, 0, v140, s[64:65]
	v_cndmask_b32_e64 v127, v22, 0, s[66:67]
	v_cndmask_b32_e64 v129, v17, 0, s[70:71]
	v_cvt_pk_bf16_f32 v15, v134, v136
	v_add_u32_e32 v22, v72, v79
	v_cvt_pk_bf16_f32 v20, v19, v20
	v_cvt_pk_bf16_f32 v21, v21, v135
	v_cndmask_b32_e64 v23, v23, 0, s[70:71]
	ds_write_b64 v22, v[14:15]
	s_waitcnt lgkmcnt(3)
	v_mfma_f32_16x16x32_bf16 v[14:17], v[10:13], v[130:133], 0
	ds_write_b64 v85, v[20:21]
	v_cvt_pk_bf16_f32 v20, v24, v126
	v_cvt_pk_bf16_f32 v21, v128, v129
	v_mfma_f32_16x16x32_bf16 v[10:13], v[10:13], v[154:157], 0
	ds_write_b64 v86, v[20:21]
	v_cvt_pk_bf16_f32 v21, v127, v23
	v_cvt_pk_bf16_f32 v20, v64, v121
	v_mfma_f32_16x16x32_bf16 v[126:129], v[142:145], v[130:133], 0
	ds_write_b64 v87, v[20:21]
	v_add_u32_e32 v64, v73, v79
	v_mov_b32_e32 v24, s29
	v_mfma_f32_16x16x32_bf16 v[130:133], v[142:145], v[154:157], 0
	v_readlane_b32 s21, v250, 14
	v_readlane_b32 s22, v250, 15
	v_readlane_b32 s23, v250, 16
	s_waitcnt lgkmcnt(5)
	v_mfma_f32_16x16x32_bf16 v[14:17], v[122:125], v[150:153], v[14:17]
	v_readlane_b32 s24, v250, 17
	v_readlane_b32 s25, v250, 18
	s_waitcnt lgkmcnt(4)
	v_mfma_f32_16x16x32_bf16 v[122:125], v[122:125], v[158:161], v[10:13]
	s_nop 2
	v_add_f32_e32 v10, 1.0, v25
	v_add_f32_e32 v11, 1.0, v65
	v_add_f32_e32 v12, 1.0, v134
	v_add_f32_e32 v13, 1.0, v136
	v_cndmask_b32_e64 v10, v25, v10, s[72:73]
	v_cndmask_b32_e64 v11, v65, v11, s[74:75]
	v_cndmask_b32_e64 v12, v134, v12, s[76:77]
	v_mfma_f32_16x16x32_bf16 v[126:129], v[146:149], v[150:153], v[126:129]
	v_cndmask_b32_e64 v13, v136, v13, s[78:79]
	v_cvt_pk_bf16_f32 v20, v10, v11
	v_cvt_pk_bf16_f32 v21, v12, v13
	ds_write_b64 v64, v[20:21]
	v_mfma_f32_16x16x32_bf16 v[130:133], v[146:149], v[158:161], v[130:133]
	v_mov_b32_e32 v20, s29
	v_cndmask_b32_e64 v21, v20, v14, s[80:81]
	v_mov_b32_e32 v14, s29
	v_cndmask_b32_e64 v25, v15, 0, s[82:83]
	v_cndmask_b32_e64 v16, 0, v16, s[86:87]
	v_cndmask_b32_e64 v17, 0, v17, s[90:91]
	v_cndmask_b32_e64 v19, v24, v122, s[80:81]
	v_cndmask_b32_e64 v23, v126, v14, s[82:83]
	v_cndmask_b32_e64 v24, v123, 0, s[82:83]
	v_cndmask_b32_e64 v122, 0, v124, s[86:87]
	v_cndmask_b32_e64 v125, 0, v125, s[90:91]
	v_cvt_pk_bf16_f32 v14, v21, v25
	v_cvt_pk_bf16_f32 v15, v16, v17
	v_cndmask_b32_e64 v121, v127, 0, s[84:85]
	v_cndmask_b32_e64 v124, v128, 0, s[88:89]
	v_cndmask_b32_e64 v127, v129, 0, s[92:93]
	ds_write_b64 v22, v[14:15] offset:2304
	v_cvt_pk_bf16_f32 v14, v19, v24
	v_cvt_pk_bf16_f32 v15, v122, v125
	v_cndmask_b32_e64 v20, v130, v20, s[82:83]
	v_cndmask_b32_e64 v65, v131, 0, s[84:85]
	v_cndmask_b32_e64 v123, v132, 0, s[88:89]
	v_cndmask_b32_e64 v126, v133, 0, s[92:93]
	ds_write_b64 v85, v[14:15] offset:2304
	v_cvt_pk_bf16_f32 v14, v23, v121
	v_cvt_pk_bf16_f32 v15, v124, v127
	ds_write_b64 v86, v[14:15] offset:2304
	v_cvt_pk_bf16_f32 v14, v20, v65
	v_cvt_pk_bf16_f32 v15, v123, v126
	v_add_f32_e32 v19, 1.0, v16
	ds_write_b64 v87, v[14:15] offset:2304
	v_add_f32_e32 v14, 1.0, v21
	v_add_f32_e32 v15, 1.0, v25
	v_cndmask_b32_e64 v16, v16, v19, s[0:1]
	v_add_f32_e32 v19, 1.0, v17
	v_cndmask_b32_e64 v14, v21, v14, s[94:95]
	v_cndmask_b32_e64 v15, v25, v15, s[96:97]
	v_cndmask_b32_e64 v17, v17, v19, s[2:3]
	v_cvt_pk_bf16_f32 v20, v14, v15
	v_cvt_pk_bf16_f32 v21, v16, v17
	ds_write_b64 v64, v[20:21] offset:2304
	s_waitcnt lgkmcnt(0)
	s_barrier
	ds_read_b64_tr_b16 v[122:123], v88
	ds_read_b64_tr_b16 v[124:125], v88 offset:576
	v_add_u32_e32 v24, v74, v79
	ds_read_b128 v[126:129], v24
	ds_read_b64_tr_b16 v[130:131], v89 offset:4608
	ds_read_b64_tr_b16 v[132:133], v89 offset:5184
	ds_read_b128 v[134:137], v24 offset:64
	v_add_u32_e32 v25, v75, v79
	s_waitcnt lgkmcnt(3)
	v_mfma_f32_16x16x32_bf16 v[126:129], v[122:125], v[126:129], 0
	ds_read_b64_tr_b16 v[138:139], v18
	ds_read_b64_tr_b16 v[140:141], v18 offset:576
	ds_read_b128 v[142:145], v25 offset:64512
	v_add_u32_e32 v21, v74, v66
	s_waitcnt lgkmcnt(3)
	v_mfma_f32_16x16x32_bf16 v[126:129], v[130:133], v[134:137], v[126:129]
	ds_read_b64_tr_b16 v[134:135], v18 offset:4608
	ds_read_b64_tr_b16 v[136:137], v18 offset:5184
	ds_read_b128 v[146:149], v25 offset:64576
	ds_read_b64_tr_b16 v[150:151], v90
	ds_read_b64_tr_b16 v[152:153], v90 offset:576
	ds_read_b64_tr_b16 v[154:155], v91 offset:4608
	ds_read_b128 v[158:161], v25 offset:55296
	ds_read_b64_tr_b16 v[156:157], v91 offset:5184
	s_waitcnt lgkmcnt(8)
	v_mfma_f32_16x16x32_bf16 v[142:145], v[138:141], v[142:145], 0
	v_add_u32_e32 v23, v75, v66
	v_add_u32_e32 v20, v76, v79
	v_add_u32_e32 v19, v76, v66
	s_waitcnt lgkmcnt(5)
	v_mfma_f32_16x16x32_bf16 v[142:145], v[134:137], v[146:149], v[142:145]
	ds_read_b128 v[146:149], v25 offset:55360
	v_add_u32_e32 v121, v77, v79
	s_waitcnt lgkmcnt(2)
	v_mfma_f32_16x16x32_bf16 v[142:145], v[150:153], v[158:161], v[142:145]
	ds_read_b128 v[158:161], v23 offset:64512
	s_waitcnt lgkmcnt(1)
	v_mfma_f32_16x16x32_bf16 v[142:145], v[154:157], v[146:149], v[142:145]
	ds_read_b128 v[146:149], v21
	s_waitcnt lgkmcnt(0)
	v_mfma_f32_16x16x32_bf16 v[122:125], v[122:125], v[146:149], 0
	ds_read_b128 v[146:149], v21 offset:64
	v_mfma_f32_16x16x32_bf16 v[138:141], v[138:141], v[158:161], 0
	v_cvt_pk_bf16_f32 v158, v126, v127
	v_cvt_pk_bf16_f32 v159, v128, v129
	s_waitcnt lgkmcnt(0)
	v_mfma_f32_16x16x32_bf16 v[122:125], v[130:133], v[146:149], v[122:125]
	ds_read_b128 v[130:133], v23 offset:64576
	ds_read_b128 v[146:149], v23 offset:55296
	ds_read_b128 v[168:171], v23 offset:55360
	s_waitcnt lgkmcnt(2)
	v_mfma_f32_16x16x32_bf16 v[126:129], v[134:137], v[130:133], v[138:141]
	v_cvt_pk_bf16_f32 v130, v142, v143
	v_cvt_pk_bf16_f32 v131, v144, v145
	ds_write2st64_b64 v20, v[158:159], v[130:131] offset0:36 offset1:54
	s_waitcnt lgkmcnt(2)
	v_mfma_f32_16x16x32_bf16 v[126:129], v[150:153], v[146:149], v[126:129]
	v_cvt_pk_bf16_f32 v130, v122, v123
	v_cvt_pk_bf16_f32 v131, v124, v125
	v_add_u32_e32 v150, v72, v66
	s_waitcnt lgkmcnt(1)
	v_mfma_f32_16x16x32_bf16 v[122:125], v[154:157], v[168:171], v[126:129]
	v_add_u32_e32 v151, v77, v66
	v_add_u32_e32 v152, v73, v66
	s_nop 5
	v_cvt_pk_bf16_f32 v122, v122, v123
	v_cvt_pk_bf16_f32 v123, v124, v125
	ds_write2st64_b64 v19, v[130:131], v[122:123] offset0:36 offset1:54
	s_waitcnt lgkmcnt(0)
	s_barrier
	ds_read_b64_tr_b16 v[122:123], v18 offset:18432
	ds_read_b64_tr_b16 v[124:125], v18 offset:19008
	ds_read_b128 v[126:129], v25 offset:18432
	ds_read_b64_tr_b16 v[130:131], v18 offset:23040
	ds_read_b64_tr_b16 v[132:133], v18 offset:23616
	ds_read_b128 v[138:141], v25 offset:18496
	ds_read_b64_tr_b16 v[142:143], v92
	ds_read_b64_tr_b16 v[144:145], v92 offset:576
	ds_read_b64_tr_b16 v[146:147], v93 offset:4608
	s_waitcnt lgkmcnt(6)
	v_mfma_f32_16x16x32_bf16 v[134:137], v[122:125], v[126:129], 0
	s_waitcnt lgkmcnt(1)
	v_mfma_f32_16x16x32_bf16 v[10:13], v[142:145], v[126:129], v[10:13]
	ds_read_b64_tr_b16 v[148:149], v93 offset:5184
	ds_read_b128 v[126:129], v23 offset:18432
	v_mfma_f32_16x16x32_bf16 v[134:137], v[130:133], v[138:141], v[134:137]
	s_waitcnt lgkmcnt(1)
	v_mfma_f32_16x16x32_bf16 v[10:13], v[146:149], v[138:141], v[10:13]
	ds_read_b128 v[138:141], v23 offset:18496
	s_nop 4
	v_cvt_pk_bf16_f32 v134, v134, v135
	v_cvt_pk_bf16_f32 v135, v136, v137
	s_waitcnt lgkmcnt(1)
	v_mfma_f32_16x16x32_bf16 v[122:125], v[122:125], v[126:129], 0
	ds_write_b64 v22, v[134:135]
	v_cvt_pk_bf16_f32 v134, v10, v11
	v_cvt_pk_bf16_f32 v135, v12, v13
	v_mfma_f32_16x16x32_bf16 v[14:17], v[142:145], v[126:129], v[14:17]
	ds_write_b64 v121, v[134:135]
	s_waitcnt lgkmcnt(2)
	v_mfma_f32_16x16x32_bf16 v[122:125], v[130:133], v[138:141], v[122:125]
	v_mfma_f32_16x16x32_bf16 v[14:17], v[146:149], v[138:141], v[14:17]
	s_nop 6
	v_cvt_pk_bf16_f32 v122, v122, v123
	v_cvt_pk_bf16_f32 v123, v124, v125
	ds_write_b64 v150, v[122:123]
	v_cvt_pk_bf16_f32 v122, v14, v15
	v_cvt_pk_bf16_f32 v123, v16, v17
	ds_write_b64 v151, v[122:123]
	s_waitcnt lgkmcnt(0)
	s_barrier
	ds_read_b64_tr_b16 v[122:123], v88
	ds_read_b64_tr_b16 v[124:125], v88 offset:576
	ds_read_b128 v[126:129], v24
	ds_read_b64_tr_b16 v[130:131], v89 offset:4608
	ds_read_b64_tr_b16 v[132:133], v89 offset:5184
	ds_read_b128 v[138:141], v24 offset:64
	ds_read_b64_tr_b16 v[142:143], v94
	ds_read_b64_tr_b16 v[144:145], v94 offset:576
	ds_read_b64_tr_b16 v[146:147], v95 offset:4608
	ds_read_b64_tr_b16 v[148:149], v95 offset:5184
	s_waitcnt lgkmcnt(7)
	v_mfma_f32_16x16x32_bf16 v[134:137], v[122:125], v[126:129], 0
	s_waitcnt lgkmcnt(2)
	v_mfma_f32_16x16x32_bf16 v[10:13], v[142:145], v[126:129], v[10:13]
	v_mfma_f32_16x16x32_bf16 v[134:137], v[130:133], v[138:141], v[134:137]
	s_waitcnt lgkmcnt(0)
	v_mfma_f32_16x16x32_bf16 v[10:13], v[146:149], v[138:141], v[10:13]
	ds_read_b128 v[126:129], v21
	ds_read_b128 v[138:141], v21 offset:64
	s_nop 3
	v_cvt_pk_bf16_f32 v134, v134, v135
	v_cvt_pk_bf16_f32 v135, v136, v137
	s_waitcnt lgkmcnt(1)
	v_mfma_f32_16x16x32_bf16 v[122:125], v[122:125], v[126:129], 0
	ds_write_b64 v20, v[134:135] offset:18432
	v_mfma_f32_16x16x32_bf16 v[14:17], v[142:145], v[126:129], v[14:17]
	s_waitcnt lgkmcnt(1)
	v_mfma_f32_16x16x32_bf16 v[122:125], v[130:133], v[138:141], v[122:125]
	v_cvt_pk_bf16_f32 v130, v10, v11
	v_cvt_pk_bf16_f32 v131, v12, v13
	ds_write_b64 v64, v[130:131]
	v_mfma_f32_16x16x32_bf16 v[14:17], v[146:149], v[138:141], v[14:17]
	s_nop 3
	v_cvt_pk_bf16_f32 v122, v122, v123
	v_cvt_pk_bf16_f32 v123, v124, v125
	ds_write_b64 v19, v[122:123] offset:18432
	s_nop 0
	v_cvt_pk_bf16_f32 v122, v14, v15
	v_cvt_pk_bf16_f32 v123, v16, v17
	ds_write_b64 v152, v[122:123]
	s_waitcnt lgkmcnt(0)
	s_barrier
	ds_read_b64_tr_b16 v[122:123], v18 offset:18432
	ds_read_b64_tr_b16 v[124:125], v18 offset:19008
	ds_read_b128 v[126:129], v25 offset:18432
	ds_read_b64_tr_b16 v[130:131], v18 offset:23040
	ds_read_b64_tr_b16 v[132:133], v18 offset:23616
	ds_read_b128 v[138:141], v25 offset:18496
	ds_read_b64_tr_b16 v[142:143], v92
	ds_read_b64_tr_b16 v[144:145], v92 offset:576
	ds_read_b64_tr_b16 v[146:147], v93 offset:4608
	ds_read_b64_tr_b16 v[148:149], v93 offset:5184
	s_waitcnt lgkmcnt(7)
	v_mfma_f32_16x16x32_bf16 v[134:137], v[122:125], v[126:129], 0
	s_waitcnt lgkmcnt(2)
	v_mfma_f32_16x16x32_bf16 v[10:13], v[142:145], v[126:129], v[10:13]
	v_mfma_f32_16x16x32_bf16 v[134:137], v[130:133], v[138:141], v[134:137]
	s_waitcnt lgkmcnt(0)
	v_mfma_f32_16x16x32_bf16 v[10:13], v[146:149], v[138:141], v[10:13]
	ds_read_b128 v[126:129], v23 offset:18432
	ds_read_b128 v[138:141], v23 offset:18496
	s_nop 3
	v_cvt_pk_bf16_f32 v134, v134, v135
	v_cvt_pk_bf16_f32 v135, v136, v137
	s_waitcnt lgkmcnt(1)
	v_mfma_f32_16x16x32_bf16 v[122:125], v[122:125], v[126:129], 0
	ds_write_b64 v22, v[134:135]
	v_mfma_f32_16x16x32_bf16 v[14:17], v[142:145], v[126:129], v[14:17]
	s_waitcnt lgkmcnt(1)
	v_mfma_f32_16x16x32_bf16 v[122:125], v[130:133], v[138:141], v[122:125]
	v_cvt_pk_bf16_f32 v130, v10, v11
	v_cvt_pk_bf16_f32 v131, v12, v13
	ds_write_b64 v121, v[130:131]
	v_mfma_f32_16x16x32_bf16 v[14:17], v[146:149], v[138:141], v[14:17]
	s_nop 3
	v_cvt_pk_bf16_f32 v122, v122, v123
	v_cvt_pk_bf16_f32 v123, v124, v125
	ds_write_b64 v150, v[122:123]
	s_nop 0
	v_cvt_pk_bf16_f32 v122, v14, v15
	v_cvt_pk_bf16_f32 v123, v16, v17
	ds_write_b64 v151, v[122:123]
	s_waitcnt lgkmcnt(0)
	s_barrier
	ds_read_b64_tr_b16 v[122:123], v88
	ds_read_b64_tr_b16 v[124:125], v88 offset:576
	ds_read_b128 v[126:129], v24
	ds_read_b64_tr_b16 v[130:131], v89 offset:4608
	ds_read_b64_tr_b16 v[132:133], v89 offset:5184
	ds_read_b128 v[138:141], v24 offset:64
	ds_read_b64_tr_b16 v[142:143], v94
	ds_read_b64_tr_b16 v[144:145], v94 offset:576
	ds_read_b64_tr_b16 v[146:147], v95 offset:4608
	ds_read_b64_tr_b16 v[148:149], v95 offset:5184
	s_waitcnt lgkmcnt(7)
	v_mfma_f32_16x16x32_bf16 v[134:137], v[122:125], v[126:129], 0
	s_waitcnt lgkmcnt(2)
	v_mfma_f32_16x16x32_bf16 v[10:13], v[142:145], v[126:129], v[10:13]
	v_mfma_f32_16x16x32_bf16 v[134:137], v[130:133], v[138:141], v[134:137]
	s_waitcnt lgkmcnt(0)
	v_mfma_f32_16x16x32_bf16 v[10:13], v[146:149], v[138:141], v[10:13]
	ds_read_b128 v[126:129], v21
	ds_read_b128 v[138:141], v21 offset:64
	s_nop 3
	v_cvt_pk_bf16_f32 v134, v134, v135
	v_cvt_pk_bf16_f32 v135, v136, v137
	s_waitcnt lgkmcnt(1)
	v_mfma_f32_16x16x32_bf16 v[122:125], v[122:125], v[126:129], 0
	ds_write_b64 v20, v[134:135] offset:18432
	v_mfma_f32_16x16x32_bf16 v[14:17], v[142:145], v[126:129], v[14:17]
	s_waitcnt lgkmcnt(1)
	v_mfma_f32_16x16x32_bf16 v[122:125], v[130:133], v[138:141], v[122:125]
	v_cvt_pk_bf16_f32 v130, v10, v11
	v_cvt_pk_bf16_f32 v131, v12, v13
	ds_write_b64 v64, v[130:131]
	v_mfma_f32_16x16x32_bf16 v[14:17], v[146:149], v[138:141], v[14:17]
	s_nop 3
	v_cvt_pk_bf16_f32 v64, v122, v123
	v_cvt_pk_bf16_f32 v65, v124, v125
	ds_write_b64 v19, v[64:65] offset:18432
	s_nop 0
	v_cvt_pk_bf16_f32 v64, v14, v15
	v_cvt_pk_bf16_f32 v65, v16, v17
	ds_write_b64 v152, v[64:65]
	s_waitcnt lgkmcnt(0)
	s_barrier
	ds_read_b64_tr_b16 v[122:123], v92
	ds_read_b64_tr_b16 v[124:125], v92 offset:576
	ds_read_b128 v[126:129], v25 offset:18432
	ds_read_b64_tr_b16 v[130:131], v93 offset:4608
	ds_read_b64_tr_b16 v[132:133], v93 offset:5184
	s_waitcnt lgkmcnt(2)
	v_mfma_f32_16x16x32_bf16 v[10:13], v[122:125], v[126:129], v[10:13]
	ds_read_b128 v[126:129], v25 offset:18496
	v_lshl_add_u64 v[64:65], s[26:27], 0, v[60:61]
	s_waitcnt lgkmcnt(0)
	v_mfma_f32_16x16x32_bf16 v[10:13], v[130:133], v[126:129], v[10:13]
	ds_read_b128 v[126:129], v23 offset:18432
	ds_read_b128 v[134:137], v23 offset:18496
	s_waitcnt lgkmcnt(1)
	v_mfma_f32_16x16x32_bf16 v[14:17], v[122:125], v[126:129], v[14:17]
	s_nop 3
	v_cvt_pk_bf16_f32 v10, v10, v11
	v_cvt_pk_bf16_f32 v11, v12, v13
	ds_write_b64 v121, v[10:11]
	s_waitcnt lgkmcnt(1)
	v_mfma_f32_16x16x32_bf16 v[10:13], v[130:133], v[134:137], v[14:17]
	s_nop 7
	v_cvt_pk_bf16_f32 v10, v10, v11
	v_cvt_pk_bf16_f32 v11, v12, v13
	ds_write_b64 v151, v[10:11]
	s_waitcnt lgkmcnt(0)
	s_barrier
	ds_read_b64_tr_b16 v[10:11], v94
	ds_read_b64_tr_b16 v[12:13], v94 offset:576
	ds_read_b128 v[14:17], v25 offset:27648
	ds_read_b64_tr_b16 v[122:123], v95 offset:4608
	ds_read_b64_tr_b16 v[124:125], v95 offset:5184
	ds_read_b128 v[126:129], v25 offset:27712
	s_waitcnt lgkmcnt(3)
	v_mfma_f32_16x16x32_bf16 v[14:17], v[10:13], v[14:17], 0
	s_waitcnt lgkmcnt(0)
	v_mfma_f32_16x16x32_bf16 v[14:17], v[122:125], v[126:129], v[14:17]
	ds_read_b128 v[126:129], v23 offset:27648
	ds_read_b128 v[130:133], v23 offset:27712
	s_waitcnt lgkmcnt(1)
	v_mfma_f32_16x16x32_bf16 v[10:13], v[10:13], v[126:129], 0
	s_nop 3
	v_cvt_pk_bf16_f32 v14, v14, v15
	v_cvt_pk_bf16_f32 v15, v16, v17
	ds_write_b64 v22, v[14:15]
	s_waitcnt lgkmcnt(1)
	v_mfma_f32_16x16x32_bf16 v[10:13], v[122:125], v[130:133], v[10:13]
	s_nop 7
	v_cvt_pk_bf16_f32 v10, v10, v11
	v_cvt_pk_bf16_f32 v11, v12, v13
	ds_write_b64 v150, v[10:11]
	s_waitcnt lgkmcnt(0)
	s_barrier
	s_cbranch_vccnz .Lscd_a
	s_waitcnt vmcnt(22)
	v_pk_mul_f32 v[46:47], v[42:43], v[40:41]
	v_mov_b32_e32 v57, v41
	s_waitcnt vmcnt(21)
	v_pk_mul_f32 v[48:49], v[44:45], v[46:47]
	v_mov_b32_e32 v56, v40
	s_waitcnt vmcnt(20)
	v_pk_mul_f32 v[50:51], v[54:55], v[48:49]
	ds_bpermute_b32 v52, v27, v50
	ds_bpermute_b32 v53, v27, v51
.Lscd_a:
	ds_read_b64_tr_b16 v[10:11], v18 offset:9216
	ds_read_b64_tr_b16 v[12:13], v18 offset:9792
	ds_read_b128 v[14:17], v25 offset:64512
	ds_read_b64_tr_b16 v[122:123], v18 offset:13824
	ds_read_b64_tr_b16 v[124:125], v18 offset:14400
	ds_read_b128 v[126:129], v25 offset:64576
	s_waitcnt lgkmcnt(3)
	v_mfma_f32_16x16x32_bf16 v[14:17], v[10:13], v[14:17], 0
	ds_read_b64_tr_b16 v[130:131], v96
	ds_read_b64_tr_b16 v[132:133], v96 offset:576
	ds_read_b128 v[134:137], v24
	s_waitcnt lgkmcnt(3)
	v_mfma_f32_16x16x32_bf16 v[14:17], v[122:125], v[126:129], v[14:17]
	ds_read_b64_tr_b16 v[126:127], v97 offset:4608
	ds_read_b64_tr_b16 v[128:129], v97 offset:5184
	ds_read_b128 v[138:141], v24 offset:64
	ds_read_b64_tr_b16 v[142:143], v98
	ds_read_b64_tr_b16 v[144:145], v98 offset:576
	ds_read_b64_tr_b16 v[146:147], v99 offset:4608
	ds_read_b128 v[150:153], v25 offset:55296
	ds_read_b64_tr_b16 v[148:149], v99 offset:5184
	ds_read_b128 v[154:157], v25 offset:55360
	ds_read_b128 v[158:161], v100 offset:36864
	ds_read_b128 v[168:171], v78
	s_waitcnt lgkmcnt(11)
	v_mfma_f32_16x16x32_bf16 v[14:17], v[130:133], v[134:137], v[14:17]
	s_waitcnt lgkmcnt(0)
	s_cbranch_vccnz .Lscd_b
	s_and_saveexec_b64 s[10:11], s[36:37]
	s_add_i32 s12, s9, 0x200
	s_and_b32 s12, s12, 0x200
	v_lshl_add_u32 v176, s12, 2, v31
	v_pk_mul_f32 v[56:57], v[40:41], v[52:53]
	v_pk_mul_f32 v[46:47], v[46:47], v[52:53]
	v_pk_mul_f32 v[48:49], v[48:49], v[52:53]
	v_pk_mul_f32 v[50:51], v[50:51], v[52:53]
	ds_write_b64 v176, v[50:51]
	s_or_b64 exec, exec, s[10:11]
	s_nop 3
.Lscd_b:
	v_pk_mul_f32 v[8:9], v[8:9], v[170:171]
	v_pk_mul_f32 v[6:7], v[6:7], v[168:169]
	v_mfma_f32_16x16x32_bf16 v[14:17], v[126:129], v[138:141], v[14:17]
	v_mul_f32_e64 v4, v4, v170
	v_mul_f32_e64 v5, v5, v171
	v_pk_mul_f32 v[2:3], v[2:3], v[168:169]
	v_mfma_f32_16x16x32_bf16 v[6:9], v[158:161], v[134:137], v[6:9]
	ds_read_b128 v[134:137], v100 offset:36928
	s_waitcnt lgkmcnt(0)
	v_mfma_f32_16x16x32_bf16 v[6:9], v[134:137], v[138:141], v[6:9]
	ds_read_b128 v[138:141], v100 offset:46080
	v_mfma_f32_16x16x32_bf16 v[14:17], v[142:145], v[150:153], v[14:17]
	s_waitcnt lgkmcnt(0)
	v_mfma_f32_16x16x32_bf16 v[6:9], v[138:141], v[150:153], v[6:9]
	ds_read_b128 v[150:153], v100 offset:46144
	v_mfma_f32_16x16x32_bf16 v[14:17], v[146:149], v[154:157], v[14:17]
	s_waitcnt lgkmcnt(0)
	v_mfma_f32_16x16x32_bf16 v[6:9], v[150:153], v[154:157], v[6:9]
	ds_read_b128 v[154:157], v23 offset:64512
	s_nop 4
	global_store_dword v[64:65], v14, off offset:-512
	global_store_dword v[64:65], v15, off offset:-256
	s_waitcnt lgkmcnt(0)
	v_mfma_f32_16x16x32_bf16 v[10:13], v[10:13], v[154:157], 0
	ds_read_b128 v[154:157], v23 offset:64576
	s_waitcnt lgkmcnt(0)
	v_mfma_f32_16x16x32_bf16 v[10:13], v[122:125], v[154:157], v[10:13]
	ds_read_b128 v[122:125], v21
	s_waitcnt lgkmcnt(0)
	v_mfma_f32_16x16x32_bf16 v[10:13], v[130:133], v[122:125], v[10:13]
	ds_read_b128 v[130:133], v21 offset:64
	v_mfma_f32_16x16x32_bf16 v[2:5], v[158:161], v[122:125], v[2:5]
	s_waitcnt lgkmcnt(0)
	v_mfma_f32_16x16x32_bf16 v[10:13], v[126:129], v[130:133], v[10:13]
	ds_read_b128 v[126:129], v23 offset:55296
	ds_read_b128 v[22:25], v23 offset:55360
	v_mfma_f32_16x16x32_bf16 v[2:5], v[134:137], v[130:133], v[2:5]
	s_waitcnt lgkmcnt(1)
	v_mfma_f32_16x16x32_bf16 v[10:13], v[142:145], v[126:129], v[10:13]
	v_mfma_f32_16x16x32_bf16 v[2:5], v[138:141], v[126:129], v[2:5]
	s_waitcnt lgkmcnt(0)
	v_mfma_f32_16x16x32_bf16 v[10:13], v[146:149], v[22:25], v[10:13]
	global_store_dword v[64:65], v16, off
	global_store_dword v[64:65], v17, off offset:256
	s_nop 5
	global_store_dword v[64:65], v10, off offset:-448
	global_store_dword v[64:65], v11, off offset:-192
	global_store_dword v[64:65], v12, off offset:64
	global_store_dword v[64:65], v13, off offset:320
	v_mfma_f32_16x16x32_bf16 v[2:5], v[150:153], v[22:25], v[2:5]
	s_branch .LBB0_861
